# LN job: ln_g/ln_b column groups 1-3 preloaded once per job instead of per token behind vmcnt(0)
# speedup vs baseline: 1.0566x; 1.0025x over previous
.LBB0_936:
	v_mov_b32_e32 v0, v178
	v_readlane_b32 s0, v228, 16
	v_ashrrev_i32_e32 v1, 4, v0
	v_and_b32_e32 v1, -4, v1
	s_add_i32 s0, s0, s8
	v_add_u32_e32 v22, s0, v1
	v_lshlrev_b32_e32 v0, 2, v0
	v_add_u32_e32 v10, -3, v22
	v_and_b32_e32 v21, 0xfc, v0
	v_and_b32_e32 v0, 64, v192
	v_ashrrev_i32_e32 v11, 31, v10
	v_add_u32_e32 v20, s8, v1
	v_add_u32_e32 v2, 64, v0
	v_lshlrev_b64 v[0:1], 12, v[10:11]
	v_lshl_add_u64 v[0:1], s[58:59], 0, v[0:1]
	v_lshlrev_b32_e32 v96, 2, v21
	v_lshl_add_u64 v[30:31], v[0:1], 0, v[96:97]
	v_xor_b32_e32 v0, 32, v192
	v_cmp_lt_i32_e32 vcc, v0, v2
	v_ashrrev_i32_e32 v9, 12, v10
	v_add_u32_e32 v8, -3, v20
	v_cndmask_b32_e32 v0, v192, v0, vcc
	v_lshlrev_b32_e32 v46, 2, v0
	v_xor_b32_e32 v0, 16, v192
	v_cmp_lt_i32_e32 vcc, v0, v2
	v_add_u32_e32 v9, s38, v9
	v_mul_hi_i32_i24_e32 v11, 0x3000, v9
	v_cndmask_b32_e32 v0, v192, v0, vcc
	v_lshlrev_b32_e32 v47, 2, v0
	v_xor_b32_e32 v0, 8, v192
	v_cmp_lt_i32_e32 vcc, v0, v2
	v_mul_i32_i24_e32 v10, 0x3000, v9
	v_ashrrev_i32_e32 v9, 31, v8
	v_cndmask_b32_e32 v0, v192, v0, vcc
	v_lshlrev_b32_e32 v49, 2, v0
	v_xor_b32_e32 v0, 4, v192
	v_cmp_lt_i32_e32 vcc, v0, v2
	v_lshlrev_b64 v[8:9], 11, v[8:9]
	v_lshl_add_u64 v[34:35], s[16:17], 0, v[10:11]
	v_cndmask_b32_e32 v0, v192, v0, vcc
	v_lshlrev_b32_e32 v50, 2, v0
	v_xor_b32_e32 v0, 2, v192
	v_cmp_lt_i32_e32 vcc, v0, v2
	v_lshl_add_u64 v[32:33], s[80:81], 0, v[8:9]
	s_mov_b64 s[0:1], 0x1000
	v_cndmask_b32_e32 v0, v192, v0, vcc
	v_lshlrev_b32_e32 v51, 2, v0
	v_xor_b32_e32 v0, 1, v192
	v_cmp_lt_i32_e32 vcc, v0, v2
	v_lshl_add_u64 v[36:37], v[34:35], 0, s[0:1]
	s_mov_b32 s0, 0x800000
	v_cndmask_b32_e32 v0, v192, v0, vcc
	v_lshlrev_b32_e32 v48, 2, v0
	global_load_dwordx4 v[232:235], v96, s[4:5] offset:1024
	global_load_dwordx4 v[236:239], v96, s[4:5] offset:2048
	global_load_dwordx4 v[240:243], v96, s[4:5] offset:3072
	global_load_dwordx4 v[244:247], v96, s[6:7] offset:1024
	global_load_dwordx4 v[248:251], v96, s[6:7] offset:2048
	global_load_dwordx4 v[252:255], v96, s[6:7] offset:3072
	global_load_dwordx4 v[0:3], v[30:31], off offset:3072
	global_load_dwordx4 v[4:7], v[30:31], off offset:2048
	global_load_dwordx4 v[16:19], v[30:31], off offset:1024
	v_readlane_b32 s10, v227, 19
	v_readlane_b32 s11, v227, 20
	s_waitcnt vmcnt(2)
	v_mov_b32_e32 v13, v0
	s_waitcnt vmcnt(1)
	v_mov_b32_e32 v12, v4
	v_mov_b32_e32 v14, v5
	v_mov_b32_e32 v15, v1
	v_pk_add_f32 v[12:13], v[12:13], v[14:15]
	v_mov_b32_e32 v14, v6
	v_mov_b32_e32 v15, v2
	v_pk_add_f32 v[12:13], v[12:13], v[14:15]
	v_mov_b32_e32 v14, v7
	v_mov_b32_e32 v15, v3
	v_pk_add_f32 v[28:29], v[12:13], v[14:15]
	global_load_dwordx4 v[24:27], v[30:31], off
	global_load_dwordx4 v[8:11], v96, s[4:5]
	global_load_dwordx4 v[12:15], v96, s[6:7]
	s_waitcnt vmcnt(3)
	v_mov_b32_e32 v39, v16
	v_mov_b32_e32 v41, v17
	s_waitcnt vmcnt(2)
	v_mov_b32_e32 v38, v24
	v_mov_b32_e32 v40, v25
	v_pk_add_f32 v[38:39], v[38:39], v[40:41]
	v_mov_b32_e32 v40, v26
	v_mov_b32_e32 v41, v18
	v_pk_add_f32 v[38:39], v[38:39], v[40:41]
	v_mov_b32_e32 v40, v27
	v_mov_b32_e32 v41, v19
	v_pk_add_f32 v[38:39], v[38:39], v[40:41]
	s_nop 0
	v_add_f32_e32 v23, 0, v38
	v_add_f32_e32 v23, v23, v39
	v_add_f32_e32 v23, v23, v28
	v_add_f32_e32 v23, v23, v29
	ds_bpermute_b32 v28, v46, v23
	s_waitcnt lgkmcnt(0)
	v_add_f32_e32 v23, v23, v28
	ds_bpermute_b32 v28, v47, v23
	s_waitcnt lgkmcnt(0)
	v_add_f32_e32 v23, v23, v28
	ds_bpermute_b32 v28, v49, v23
	s_waitcnt lgkmcnt(0)
	v_add_f32_e32 v23, v23, v28
	ds_bpermute_b32 v28, v50, v23
	s_waitcnt lgkmcnt(0)
	v_add_f32_e32 v23, v23, v28
	ds_bpermute_b32 v28, v51, v23
	s_waitcnt lgkmcnt(0)
	v_add_f32_e32 v23, v23, v28
	ds_bpermute_b32 v28, v48, v23
	s_waitcnt lgkmcnt(0)
	v_add_f32_e32 v23, v23, v28
	v_mul_f32_e32 v42, 0x3a800000, v23
	v_pk_add_f32 v[24:25], v[24:25], v[42:43] op_sel_hi:[1,0] neg_lo:[0,1] neg_hi:[0,1]
	v_pk_add_f32 v[44:45], v[26:27], v[42:43] op_sel_hi:[1,0] neg_lo:[0,1] neg_hi:[0,1]
	v_pk_add_f32 v[26:27], v[16:17], v[42:43] op_sel_hi:[1,0] neg_lo:[0,1] neg_hi:[0,1]
	v_pk_add_f32 v[28:29], v[18:19], v[42:43] op_sel_hi:[1,0] neg_lo:[0,1] neg_hi:[0,1]
	v_mov_b32_e32 v18, v25
	v_mov_b32_e32 v19, v27
	v_pk_add_f32 v[38:39], v[4:5], v[42:43] op_sel_hi:[1,0] neg_lo:[0,1] neg_hi:[0,1]
	v_pk_add_f32 v[4:5], v[0:1], v[42:43] op_sel_hi:[1,0] neg_lo:[0,1] neg_hi:[0,1]
	v_mov_b32_e32 v16, v24
	v_mov_b32_e32 v17, v26
	v_pk_mul_f32 v[18:19], v[18:19], v[18:19]
	v_pk_add_f32 v[40:41], v[6:7], v[42:43] op_sel_hi:[1,0] neg_lo:[0,1] neg_hi:[0,1]
	v_pk_add_f32 v[6:7], v[2:3], v[42:43] op_sel_hi:[1,0] neg_lo:[0,1] neg_hi:[0,1]
	v_mov_b32_e32 v2, v5
	v_mov_b32_e32 v3, v39
	v_pk_fma_f32 v[16:17], v[16:17], v[16:17], v[18:19]
	v_mov_b32_e32 v18, v44
	v_mov_b32_e32 v19, v28
	v_mov_b32_e32 v0, v4
	v_mov_b32_e32 v1, v38
	v_pk_mul_f32 v[2:3], v[2:3], v[2:3]
	v_pk_fma_f32 v[16:17], v[18:19], v[18:19], v[16:17]
	v_mov_b32_e32 v18, v45
	v_mov_b32_e32 v19, v29
	v_pk_fma_f32 v[0:1], v[0:1], v[0:1], v[2:3]
	v_mov_b32_e32 v2, v6
	v_mov_b32_e32 v3, v40
	v_pk_fma_f32 v[16:17], v[18:19], v[18:19], v[16:17]
	v_pk_fma_f32 v[0:1], v[2:3], v[2:3], v[0:1]
	v_mov_b32_e32 v2, v7
	v_mov_b32_e32 v3, v41
	v_pk_fma_f32 v[0:1], v[2:3], v[2:3], v[0:1]
	v_add_f32_e32 v2, v16, v17
	v_add_f32_e32 v1, v1, v2
	v_add_f32_e32 v0, v0, v1
	ds_bpermute_b32 v1, v46, v0
	v_lshlrev_b32_e32 v16, 1, v21
	s_waitcnt lgkmcnt(0)
	v_add_f32_e32 v0, v0, v1
	ds_bpermute_b32 v1, v47, v0
	s_waitcnt lgkmcnt(0)
	v_add_f32_e32 v0, v0, v1
	ds_bpermute_b32 v1, v49, v0
	s_waitcnt lgkmcnt(0)
	v_add_f32_e32 v0, v0, v1
	ds_bpermute_b32 v1, v50, v0
	s_waitcnt lgkmcnt(0)
	v_add_f32_e32 v0, v0, v1
	ds_bpermute_b32 v1, v51, v0
	s_waitcnt lgkmcnt(0)
	v_add_f32_e32 v0, v0, v1
	ds_bpermute_b32 v1, v48, v0
	s_waitcnt lgkmcnt(0)
	v_add_f32_e32 v0, v0, v1
	v_fmamk_f32 v0, v0, 0x3a800000, v181
	v_cmp_gt_f32_e32 vcc, s0, v0
	v_mul_f32_e32 v1, 0x4b800000, v0
	s_nop 0
	v_cndmask_b32_e32 v0, v0, v1, vcc
	v_rsq_f32_e32 v0, v0
	s_nop 0
	v_mul_f32_e32 v1, 0x45800000, v0
	v_cndmask_b32_e32 v42, v0, v1, vcc
	v_pk_mul_f32 v[0:1], v[24:25], v[42:43] op_sel_hi:[1,0]
	v_pk_mul_f32 v[2:3], v[44:45], v[42:43] op_sel_hi:[1,0]
	s_waitcnt vmcnt(0)
	v_pk_fma_f32 v[0:1], v[8:9], v[0:1], v[12:13]
	v_cndmask_b32_e64 v8, 0, 1, s[10:11]
	v_pk_fma_f32 v[2:3], v[10:11], v[2:3], v[14:15]
	v_cmp_ne_u32_e64 s[0:1], 1, v8
	s_andn2_b64 vcc, exec, s[10:11]
	global_store_dwordx4 v[30:31], v[0:3], off
	s_cbranch_vccnz .LBB0_938
	v_lshl_add_u64 v[8:9], v[36:37], 0, v[96:97]
	global_load_dwordx4 v[8:11], v[8:9], off
	v_lshl_add_u64 v[12:13], v[34:35], 0, v[96:97]
	global_load_dwordx4 v[12:15], v[12:13], off
	v_mov_b32_e32 v17, v97
	s_waitcnt vmcnt(1)
	v_add_f32_e32 v8, 1.0, v8
	v_add_f32_e32 v9, 1.0, v9
	v_add_f32_e32 v10, 1.0, v10
	v_add_f32_e32 v11, 1.0, v11
	s_waitcnt vmcnt(0)
	v_fma_f32 v0, v0, v8, v12
	v_fma_f32 v1, v1, v9, v13
	v_fma_f32 v2, v2, v10, v14
	v_fmac_f32_e32 v15, v3, v11
	v_cvt_pk_bf16_f32 v0, v0, v1
	v_cvt_pk_bf16_f32 v1, v2, v15
	v_lshl_add_u64 v[2:3], v[32:33], 0, v[16:17]
	global_store_dwordx2 v[2:3], v[0:1], off
.LBB0_938:
	v_lshl_add_u64 v[24:25], s[4:5], 0, v[96:97]
	v_lshl_add_u64 v[18:19], s[6:7], 0, v[96:97]
	v_mov_b32_e32 v0, v232
	v_mov_b32_e32 v1, v233
	v_mov_b32_e32 v2, v234
	v_mov_b32_e32 v3, v235
	v_mov_b32_e32 v8, v244
	v_mov_b32_e32 v9, v245
	v_mov_b32_e32 v10, v246
	v_mov_b32_e32 v11, v247
	v_mov_b32_e32 v43, v42
	v_or_b32_e32 v17, 0x100, v21
	v_pk_mul_f32 v[12:13], v[26:27], v[42:43]
	v_pk_mul_f32 v[14:15], v[28:29], v[42:43]
	s_and_b64 vcc, exec, s[0:1]
	v_lshlrev_b32_e32 v26, 2, v17
	v_pk_fma_f32 v[0:1], v[12:13], v[0:1], v[8:9]
	v_pk_fma_f32 v[2:3], v[14:15], v[2:3], v[10:11]
	global_store_dwordx4 v[30:31], v[0:3], off offset:1024
	s_cbranch_vccnz .LBB0_940
	v_mov_b32_e32 v27, v97
	v_lshl_add_u64 v[8:9], v[36:37], 0, v[26:27]
	global_load_dwordx4 v[8:11], v[8:9], off
	v_lshl_add_u64 v[12:13], v[34:35], 0, v[96:97]
	global_load_dwordx4 v[12:15], v[12:13], off offset:1024
	v_mov_b32_e32 v17, v97
	s_waitcnt vmcnt(1)
	v_add_f32_e32 v8, 1.0, v8
	v_add_f32_e32 v9, 1.0, v9
	v_add_f32_e32 v10, 1.0, v10
	v_add_f32_e32 v11, 1.0, v11
	s_waitcnt vmcnt(0)
	v_fma_f32 v0, v0, v8, v12
	v_fma_f32 v1, v1, v9, v13
	v_fma_f32 v2, v2, v10, v14
	v_fmac_f32_e32 v15, v3, v11
	v_cvt_pk_bf16_f32 v0, v0, v1
	v_cvt_pk_bf16_f32 v1, v2, v15
	v_lshl_add_u64 v[2:3], v[32:33], 0, v[16:17]
	global_store_dwordx2 v[2:3], v[0:1], off offset:512
.LBB0_940:
	v_mov_b32_e32 v0, v236
	v_mov_b32_e32 v1, v237
	v_mov_b32_e32 v2, v238
	v_mov_b32_e32 v3, v239
	s_nop 0
	v_mov_b32_e32 v8, v248
	v_mov_b32_e32 v9, v249
	v_mov_b32_e32 v10, v250
	v_mov_b32_e32 v11, v251
	v_or_b32_e32 v17, 0x200, v21
	v_pk_mul_f32 v[12:13], v[38:39], v[42:43]
	v_pk_mul_f32 v[14:15], v[40:41], v[42:43]
	s_and_b64 vcc, exec, s[0:1]
	v_lshlrev_b32_e32 v28, 2, v17
	v_pk_fma_f32 v[0:1], v[12:13], v[0:1], v[8:9]
	v_pk_fma_f32 v[2:3], v[14:15], v[2:3], v[10:11]
	global_store_dwordx4 v[30:31], v[0:3], off offset:2048
	s_cbranch_vccnz .LBB0_942
	v_mov_b32_e32 v29, v97
	v_lshl_add_u64 v[8:9], v[36:37], 0, v[28:29]
	global_load_dwordx4 v[8:11], v[8:9], off
	v_lshl_add_u64 v[12:13], v[34:35], 0, v[96:97]
	global_load_dwordx4 v[12:15], v[12:13], off offset:2048
	v_mov_b32_e32 v17, v97
	s_waitcnt vmcnt(1)
	v_add_f32_e32 v8, 1.0, v8
	v_add_f32_e32 v9, 1.0, v9
	v_add_f32_e32 v10, 1.0, v10
	v_add_f32_e32 v11, 1.0, v11
	s_waitcnt vmcnt(0)
	v_fma_f32 v0, v0, v8, v12
	v_fma_f32 v1, v1, v9, v13
	v_fma_f32 v2, v2, v10, v14
	v_fmac_f32_e32 v15, v3, v11
	v_cvt_pk_bf16_f32 v0, v0, v1
	v_cvt_pk_bf16_f32 v1, v2, v15
	v_lshl_add_u64 v[2:3], v[32:33], 0, v[16:17]
	global_store_dwordx2 v[2:3], v[0:1], off offset:1024
.LBB0_942:
	v_pk_mul_f32 v[8:9], v[4:5], v[42:43]
	v_pk_mul_f32 v[10:11], v[6:7], v[42:43]
	v_mov_b32_e32 v0, v240
	v_mov_b32_e32 v1, v241
	v_mov_b32_e32 v2, v242
	v_mov_b32_e32 v3, v243
	v_mov_b32_e32 v4, v252
	v_mov_b32_e32 v5, v253
	v_mov_b32_e32 v6, v254
	v_mov_b32_e32 v7, v255
	v_or_b32_e32 v12, 0x300, v21
	s_and_b64 vcc, exec, s[0:1]
	v_pk_fma_f32 v[0:1], v[8:9], v[0:1], v[4:5]
	v_pk_fma_f32 v[2:3], v[10:11], v[2:3], v[6:7]
	global_store_dwordx4 v[30:31], v[0:3], off offset:3072
	v_lshlrev_b32_e32 v30, 2, v12
	s_cbranch_vccnz .LBB0_944
	v_mov_b32_e32 v31, v97
	v_lshl_add_u64 v[4:5], v[36:37], 0, v[30:31]
	global_load_dwordx4 v[4:7], v[4:5], off
	v_lshl_add_u64 v[8:9], v[34:35], 0, v[96:97]
	global_load_dwordx4 v[8:11], v[8:9], off offset:3072
	v_mov_b32_e32 v17, v97
	s_waitcnt vmcnt(1)
	v_add_f32_e32 v4, 1.0, v4
	v_add_f32_e32 v5, 1.0, v5
	v_add_f32_e32 v6, 1.0, v6
	v_add_f32_e32 v7, 1.0, v7
	s_waitcnt vmcnt(0)
	v_fma_f32 v0, v0, v4, v8
	v_fma_f32 v1, v1, v5, v9
	v_fma_f32 v2, v2, v6, v10
	v_fmac_f32_e32 v11, v3, v7
	v_cvt_pk_bf16_f32 v0, v0, v1
	v_cvt_pk_bf16_f32 v1, v2, v11
	v_lshl_add_u64 v[2:3], v[32:33], 0, v[16:17]
	global_store_dwordx2 v[2:3], v[0:1], off offset:1536

.LBB0_946:
	v_mov_b32_e32 v0, v232
	v_mov_b32_e32 v1, v233
	v_mov_b32_e32 v2, v234
	v_mov_b32_e32 v3, v235
	s_nop 0
	v_mov_b32_e32 v4, v244
	v_mov_b32_e32 v5, v245
	v_mov_b32_e32 v6, v246
	v_mov_b32_e32 v7, v247
	v_mov_b32_e32 v45, v44
	v_pk_mul_f32 v[40:41], v[40:41], v[44:45]
	v_pk_mul_f32 v[42:43], v[42:43], v[44:45]
	s_and_b64 vcc, exec, s[0:1]
	v_pk_fma_f32 v[0:1], v[40:41], v[0:1], v[4:5]
	v_pk_fma_f32 v[2:3], v[42:43], v[2:3], v[6:7]
	global_store_dwordx4 v[34:35], v[0:3], off offset:1024
	s_cbranch_vccnz .LBB0_948
	v_mov_b32_e32 v27, v97
	v_lshl_add_u64 v[4:5], v[38:39], 0, v[26:27]
	global_load_dwordx4 v[4:7], v[4:5], off
	v_lshl_add_u64 v[40:41], v[36:37], 0, v[96:97]
	global_load_dwordx4 v[40:43], v[40:41], off offset:1024
	v_mov_b32_e32 v17, v97
	s_waitcnt vmcnt(1)
	v_add_f32_e32 v4, 1.0, v4
	v_add_f32_e32 v5, 1.0, v5
	v_add_f32_e32 v6, 1.0, v6
	v_add_f32_e32 v7, 1.0, v7
	s_waitcnt vmcnt(0)
	v_fma_f32 v0, v0, v4, v40
	v_fma_f32 v1, v1, v5, v41
	v_fma_f32 v2, v2, v6, v42
	v_fmac_f32_e32 v43, v3, v7
	v_cvt_pk_bf16_f32 v0, v0, v1
	v_cvt_pk_bf16_f32 v1, v2, v43
	v_lshl_add_u64 v[2:3], v[32:33], 0, v[16:17]
	global_store_dwordx2 v[2:3], v[0:1], off offset:512
.LBB0_948:
	v_mov_b32_e32 v0, v236
	v_mov_b32_e32 v1, v237
	v_mov_b32_e32 v2, v238
	v_mov_b32_e32 v3, v239
	s_nop 0
	v_mov_b32_e32 v4, v248
	v_mov_b32_e32 v5, v249
	v_mov_b32_e32 v6, v250
	v_mov_b32_e32 v7, v251
	v_pk_mul_f32 v[12:13], v[12:13], v[44:45]
	v_pk_mul_f32 v[14:15], v[14:15], v[44:45]
	s_and_b64 vcc, exec, s[0:1]
	v_pk_fma_f32 v[0:1], v[12:13], v[0:1], v[4:5]
	v_pk_fma_f32 v[2:3], v[14:15], v[2:3], v[6:7]
	global_store_dwordx4 v[34:35], v[0:3], off offset:2048
	s_cbranch_vccnz .LBB0_950
	v_mov_b32_e32 v29, v97
	v_lshl_add_u64 v[4:5], v[38:39], 0, v[28:29]
	global_load_dwordx4 v[4:7], v[4:5], off
	v_lshl_add_u64 v[12:13], v[36:37], 0, v[96:97]
	global_load_dwordx4 v[12:15], v[12:13], off offset:2048
	v_mov_b32_e32 v17, v97
	s_waitcnt vmcnt(1)
	v_add_f32_e32 v4, 1.0, v4
	v_add_f32_e32 v5, 1.0, v5
	v_add_f32_e32 v6, 1.0, v6
	v_add_f32_e32 v7, 1.0, v7
	s_waitcnt vmcnt(0)
	v_fma_f32 v0, v0, v4, v12
	v_fma_f32 v1, v1, v5, v13
	v_fma_f32 v2, v2, v6, v14
	v_fmac_f32_e32 v15, v3, v7
	v_cvt_pk_bf16_f32 v0, v0, v1
	v_cvt_pk_bf16_f32 v1, v2, v15
	v_lshl_add_u64 v[2:3], v[32:33], 0, v[16:17]
	global_store_dwordx2 v[2:3], v[0:1], off offset:1024
.LBB0_950:
	v_mov_b32_e32 v0, v240
	v_mov_b32_e32 v1, v241
	v_mov_b32_e32 v2, v242
	v_mov_b32_e32 v3, v243
	s_nop 0
	v_mov_b32_e32 v4, v252
	v_mov_b32_e32 v5, v253
	v_mov_b32_e32 v6, v254
	v_mov_b32_e32 v7, v255
	v_pk_mul_f32 v[8:9], v[8:9], v[44:45]
	v_pk_mul_f32 v[10:11], v[10:11], v[44:45]
	s_and_b64 vcc, exec, s[0:1]
	v_pk_fma_f32 v[0:1], v[8:9], v[0:1], v[4:5]
	v_pk_fma_f32 v[2:3], v[10:11], v[2:3], v[6:7]
	global_store_dwordx4 v[34:35], v[0:3], off offset:3072
	s_cbranch_vccnz .LBB0_952
	v_mov_b32_e32 v31, v97
	v_lshl_add_u64 v[4:5], v[38:39], 0, v[30:31]
	global_load_dwordx4 v[4:7], v[4:5], off
	v_lshl_add_u64 v[8:9], v[36:37], 0, v[96:97]
	global_load_dwordx4 v[8:11], v[8:9], off offset:3072
	v_mov_b32_e32 v17, v97
	s_waitcnt vmcnt(1)
	v_add_f32_e32 v4, 1.0, v4
	v_add_f32_e32 v5, 1.0, v5
	v_add_f32_e32 v6, 1.0, v6
	v_add_f32_e32 v7, 1.0, v7
	s_waitcnt vmcnt(0)
	v_fma_f32 v0, v0, v4, v8
	v_fma_f32 v1, v1, v5, v9
	v_fma_f32 v2, v2, v6, v10
	v_fmac_f32_e32 v11, v3, v7
	v_cvt_pk_bf16_f32 v0, v0, v1
	v_cvt_pk_bf16_f32 v1, v2, v11
	v_lshl_add_u64 v[2:3], v[32:33], 0, v[16:17]
	global_store_dwordx2 v[2:3], v[0:1], off offset:1536

.LBB0_962:
	v_mov_b32_e32 v0, v232
	v_mov_b32_e32 v1, v233
	v_mov_b32_e32 v2, v234
	v_mov_b32_e32 v3, v235
	s_nop 0
	v_mov_b32_e32 v4, v244
	v_mov_b32_e32 v5, v245
	v_mov_b32_e32 v6, v246
	v_mov_b32_e32 v7, v247
	v_mov_b32_e32 v41, v40
	v_pk_mul_f32 v[36:37], v[36:37], v[40:41]
	v_pk_mul_f32 v[38:39], v[38:39], v[40:41]
	s_and_b64 vcc, exec, s[0:1]
	v_pk_fma_f32 v[0:1], v[36:37], v[0:1], v[4:5]
	v_pk_fma_f32 v[2:3], v[38:39], v[2:3], v[6:7]
	global_store_dwordx4 v[32:33], v[0:3], off offset:1024
	s_cbranch_vccnz .LBB0_964
	v_mov_b32_e32 v27, v97
	v_lshl_add_u64 v[4:5], v[34:35], 0, v[26:27]
	global_load_dwordx4 v[4:7], v[4:5], off
	v_lshl_add_u64 v[26:27], v[22:23], 0, v[96:97]
	global_load_dwordx4 v[36:39], v[26:27], off offset:1024
	v_mov_b32_e32 v17, v97
	s_waitcnt vmcnt(1)
	v_add_f32_e32 v4, 1.0, v4
	v_add_f32_e32 v5, 1.0, v5
	v_add_f32_e32 v6, 1.0, v6
	v_add_f32_e32 v7, 1.0, v7
	s_waitcnt vmcnt(0)
	v_fma_f32 v0, v0, v4, v36
	v_fma_f32 v1, v1, v5, v37
	v_fma_f32 v2, v2, v6, v38
	v_fmac_f32_e32 v39, v3, v7
	v_cvt_pk_bf16_f32 v0, v0, v1
	v_cvt_pk_bf16_f32 v1, v2, v39
	v_lshl_add_u64 v[2:3], v[20:21], 0, v[16:17]
	global_store_dwordx2 v[2:3], v[0:1], off offset:512
.LBB0_964:
	v_mov_b32_e32 v0, v236
	v_mov_b32_e32 v1, v237
	v_mov_b32_e32 v2, v238
	v_mov_b32_e32 v3, v239
	s_nop 0
	v_mov_b32_e32 v4, v248
	v_mov_b32_e32 v5, v249
	v_mov_b32_e32 v6, v250
	v_mov_b32_e32 v7, v251
	v_pk_mul_f32 v[12:13], v[12:13], v[40:41]
	v_pk_mul_f32 v[14:15], v[14:15], v[40:41]
	s_and_b64 vcc, exec, s[0:1]
	v_pk_fma_f32 v[0:1], v[12:13], v[0:1], v[4:5]
	v_pk_fma_f32 v[2:3], v[14:15], v[2:3], v[6:7]
	global_store_dwordx4 v[32:33], v[0:3], off offset:2048
	s_cbranch_vccnz .LBB0_966
	v_mov_b32_e32 v29, v97
	v_lshl_add_u64 v[4:5], v[34:35], 0, v[28:29]
	global_load_dwordx4 v[4:7], v[4:5], off
	v_lshl_add_u64 v[12:13], v[22:23], 0, v[96:97]
	global_load_dwordx4 v[12:15], v[12:13], off offset:2048
	v_mov_b32_e32 v17, v97
	s_waitcnt vmcnt(1)
	v_add_f32_e32 v4, 1.0, v4
	v_add_f32_e32 v5, 1.0, v5
	v_add_f32_e32 v6, 1.0, v6
	v_add_f32_e32 v7, 1.0, v7
	s_waitcnt vmcnt(0)
	v_fma_f32 v0, v0, v4, v12
	v_fma_f32 v1, v1, v5, v13
	v_fma_f32 v2, v2, v6, v14
	v_fmac_f32_e32 v15, v3, v7
	v_cvt_pk_bf16_f32 v0, v0, v1
	v_cvt_pk_bf16_f32 v1, v2, v15
	v_lshl_add_u64 v[2:3], v[20:21], 0, v[16:17]
	global_store_dwordx2 v[2:3], v[0:1], off offset:1024
.LBB0_966:
	v_mov_b32_e32 v0, v240
	v_mov_b32_e32 v1, v241
	v_mov_b32_e32 v2, v242
	v_mov_b32_e32 v3, v243
	s_nop 0
	v_mov_b32_e32 v4, v252
	v_mov_b32_e32 v5, v253
	v_mov_b32_e32 v6, v254
	v_mov_b32_e32 v7, v255
	v_pk_mul_f32 v[8:9], v[8:9], v[40:41]
	v_pk_mul_f32 v[10:11], v[10:11], v[40:41]
	s_and_b64 vcc, exec, s[0:1]
	v_pk_fma_f32 v[0:1], v[8:9], v[0:1], v[4:5]
	v_pk_fma_f32 v[2:3], v[10:11], v[2:3], v[6:7]
	global_store_dwordx4 v[32:33], v[0:3], off offset:3072
	s_cbranch_vccnz .LBB0_935
	v_mov_b32_e32 v31, v97
	v_lshl_add_u64 v[4:5], v[34:35], 0, v[30:31]
	global_load_dwordx4 v[4:7], v[4:5], off
	v_lshl_add_u64 v[8:9], v[22:23], 0, v[96:97]
	global_load_dwordx4 v[8:11], v[8:9], off offset:3072
	v_mov_b32_e32 v17, v97
	s_waitcnt vmcnt(1)
	v_add_f32_e32 v4, 1.0, v4
	v_add_f32_e32 v5, 1.0, v5
	v_add_f32_e32 v6, 1.0, v6
	v_add_f32_e32 v7, 1.0, v7
	s_waitcnt vmcnt(0)
	v_fma_f32 v0, v0, v4, v8
	v_fma_f32 v1, v1, v5, v9
	v_fma_f32 v2, v2, v6, v10
	v_fmac_f32_e32 v11, v3, v7
	v_cvt_pk_bf16_f32 v0, v0, v1
	v_cvt_pk_bf16_f32 v1, v2, v11
	v_lshl_add_u64 v[2:3], v[20:21], 0, v[16:17]
	global_store_dwordx2 v[2:3], v[0:1], off offset:1536
	s_branch .LBB0_935
